# same as previous but grid barrier keeps the original late acquire invalidate (conservative variant)
# baseline (speedup 1.0000x reference)
.LBB0_118:
	ds_read_b128 v[4:7], v150 offset:32768
	ds_read_b128 v[174:177], v150 offset:34816
	ds_read_b128 v[178:181], v150 offset:36864
	ds_read_b128 v[212:215], v151 offset:49152
	ds_read_b128 v[216:219], v151 offset:51200
	ds_read_b128 v[220:223], v151 offset:53248
	ds_read_b128 v[234:237], v151 offset:55296
	s_waitcnt lgkmcnt(0)
	v_mfma_f32_16x16x32_bf16 v[48:51], v[212:215], v[4:7], v[48:51]
	v_mfma_f32_16x16x32_bf16 v[8:11], v[216:219], v[4:7], v[8:11]
	v_mfma_f32_16x16x32_bf16 v[12:15], v[220:223], v[4:7], v[12:15]
	v_mfma_f32_16x16x32_bf16 v[4:7], v[234:237], v[4:7], v[16:19]
	v_mfma_f32_16x16x32_bf16 v[20:23], v[212:215], v[174:177], v[20:23]
	v_mfma_f32_16x16x32_bf16 v[24:27], v[216:219], v[174:177], v[24:27]
	v_mfma_f32_16x16x32_bf16 v[28:31], v[220:223], v[174:177], v[28:31]
	v_mfma_f32_16x16x32_bf16 v[32:35], v[234:237], v[174:177], v[32:35]
	v_mfma_f32_16x16x32_bf16 v[36:39], v[212:215], v[178:181], v[36:39]
	v_mfma_f32_16x16x32_bf16 v[40:43], v[216:219], v[178:181], v[40:43]
	v_mfma_f32_16x16x32_bf16 v[44:47], v[220:223], v[178:181], v[44:47]
	v_mfma_f32_16x16x32_bf16 v[174:177], v[234:237], v[178:181], v[0:3]
	ds_read_b128 v[16:19], v155 offset:32768
	ds_read_b128 v[178:181], v155 offset:34816
	ds_read_b128 v[212:215], v155 offset:36864
	ds_read_b128 v[216:219], v157 offset:49152
	ds_read_b128 v[220:223], v157 offset:51200
	ds_read_b128 v[234:237], v157 offset:53248
	ds_read_b128 v[238:241], v157 offset:55296
	s_waitcnt lgkmcnt(0)
	v_mfma_f32_16x16x32_bf16 v[0:3], v[216:219], v[16:19], v[48:51]
	s_nop 0
	v_mfma_f32_16x16x32_bf16 v[8:11], v[220:223], v[16:19], v[8:11]
	v_mfma_f32_16x16x32_bf16 v[12:15], v[234:237], v[16:19], v[12:15]
	v_mfma_f32_16x16x32_bf16 v[16:19], v[238:241], v[16:19], v[4:7]
	v_mfma_f32_16x16x32_bf16 v[20:23], v[216:219], v[178:181], v[20:23]
	v_mfma_f32_16x16x32_bf16 v[24:27], v[220:223], v[178:181], v[24:27]
	v_mfma_f32_16x16x32_bf16 v[28:31], v[234:237], v[178:181], v[28:31]
	v_mfma_f32_16x16x32_bf16 v[32:35], v[238:241], v[178:181], v[32:35]
	v_mfma_f32_16x16x32_bf16 v[36:39], v[216:219], v[212:215], v[36:39]
	v_mfma_f32_16x16x32_bf16 v[40:43], v[220:223], v[212:215], v[40:43]
	v_mfma_f32_16x16x32_bf16 v[44:47], v[234:237], v[212:215], v[44:47]
	v_mfma_f32_16x16x32_bf16 v[4:7], v[238:241], v[212:215], v[174:177]
	s_not_b64 s[40:41], s[2:3]
	s_andn2_b64 vcc, exec, s[2:3]
	s_cbranch_vccnz .Lmg_last
	v_lshlrev_b32_e32 v65, 16, v140
	v_and_b32_e32 v67, 0xffff0000, v140
	v_lshlrev_b32_e32 v69, 16, v141
	v_and_b32_e32 v71, 0xffff0000, v141
	v_mul_f32_e32 v65, 0xbfb8aa3b, v65
	v_mul_f32_e32 v67, 0xbfb8aa3b, v67
	v_mul_f32_e32 v69, 0xbfb8aa3b, v69
	v_mul_f32_e32 v71, 0xbfb8aa3b, v71
	v_exp_f32_e32 v65, v65
	v_exp_f32_e32 v67, v67
	v_exp_f32_e32 v69, v69
	v_exp_f32_e32 v71, v71
	v_add_f32_e32 v65, 1.0, v65
	v_add_f32_e32 v67, 1.0, v67
	v_add_f32_e32 v69, 1.0, v69
	v_add_f32_e32 v71, 1.0, v71
	v_rcp_f32_e32 v65, v65
	v_rcp_f32_e32 v67, v67
	v_rcp_f32_e32 v69, v69
	v_rcp_f32_e32 v71, v71
	v_max_f32_e32 v48, 0x358637bd, v65
	v_max_f32_e32 v49, 0x358637bd, v67
	v_max_f32_e32 v50, 0x358637bd, v69
	v_max_f32_e32 v51, 0x358637bd, v71
	v_lshlrev_b32_e32 v65, 16, v102
	v_and_b32_e32 v67, 0xffff0000, v102
	v_lshlrev_b32_e32 v69, 16, v103
	v_and_b32_e32 v71, 0xffff0000, v103
	v_mul_f32_e32 v65, 0xbfb8aa3b, v65
	v_mul_f32_e32 v67, 0xbfb8aa3b, v67
	v_mul_f32_e32 v69, 0xbfb8aa3b, v69
	v_mul_f32_e32 v71, 0xbfb8aa3b, v71
	v_exp_f32_e32 v65, v65
	v_exp_f32_e32 v67, v67
	v_exp_f32_e32 v69, v69
	v_exp_f32_e32 v71, v71
	v_add_f32_e32 v65, 1.0, v65
	v_add_f32_e32 v67, 1.0, v67
	v_add_f32_e32 v69, 1.0, v69
	v_add_f32_e32 v71, 1.0, v71
	v_min_f32_e32 v65, 0x49742400, v65
	v_min_f32_e32 v67, 0x49742400, v67
	v_min_f32_e32 v69, 0x49742400, v69
	v_min_f32_e32 v71, 0x49742400, v71
	v_mul_f32_e32 v48, v48, v65
	v_mul_f32_e32 v49, v49, v67
	v_mul_f32_e32 v50, v50, v69
	v_mul_f32_e32 v51, v51, v71
	v_lshlrev_b32_e32 v65, 16, v106
	v_and_b32_e32 v67, 0xffff0000, v106
	v_lshlrev_b32_e32 v69, 16, v107
	v_and_b32_e32 v71, 0xffff0000, v107
	v_mul_f32_e32 v65, 0xbfb8aa3b, v65
	v_mul_f32_e32 v67, 0xbfb8aa3b, v67
	v_mul_f32_e32 v69, 0xbfb8aa3b, v69
	v_mul_f32_e32 v71, 0xbfb8aa3b, v71
	v_exp_f32_e32 v65, v65
	v_exp_f32_e32 v67, v67
	v_exp_f32_e32 v69, v69
	v_exp_f32_e32 v71, v71
	v_add_f32_e32 v65, 1.0, v65
	v_add_f32_e32 v67, 1.0, v67
	v_add_f32_e32 v69, 1.0, v69
	v_add_f32_e32 v71, 1.0, v71
	v_rcp_f32_e32 v65, v65
	v_rcp_f32_e32 v67, v67
	v_rcp_f32_e32 v69, v69
	v_rcp_f32_e32 v71, v71
	v_max_f32_e32 v102, 0x358637bd, v65
	v_max_f32_e32 v103, 0x358637bd, v67
	v_max_f32_e32 v106, 0x358637bd, v69
	v_max_f32_e32 v107, 0x358637bd, v71
	v_lshlrev_b32_e32 v65, 16, v110
	v_and_b32_e32 v67, 0xffff0000, v110
	v_lshlrev_b32_e32 v69, 16, v111
	v_and_b32_e32 v71, 0xffff0000, v111
	v_mul_f32_e32 v65, 0xbfb8aa3b, v65
	v_mul_f32_e32 v67, 0xbfb8aa3b, v67
	v_mul_f32_e32 v69, 0xbfb8aa3b, v69
	v_mul_f32_e32 v71, 0xbfb8aa3b, v71
	v_exp_f32_e32 v65, v65
	v_exp_f32_e32 v67, v67
	v_exp_f32_e32 v69, v69
	v_exp_f32_e32 v71, v71
	v_add_f32_e32 v65, 1.0, v65
	v_add_f32_e32 v67, 1.0, v67
	v_add_f32_e32 v69, 1.0, v69
	v_add_f32_e32 v71, 1.0, v71
	v_min_f32_e32 v65, 0x49742400, v65
	v_min_f32_e32 v67, 0x49742400, v67
	v_min_f32_e32 v69, 0x49742400, v69
	v_min_f32_e32 v71, 0x49742400, v71
	v_mul_f32_e32 v102, v102, v65
	v_mul_f32_e32 v103, v103, v67
	v_mul_f32_e32 v106, v106, v69
	v_mul_f32_e32 v107, v107, v71
	v_lshlrev_b32_e32 v65, 16, v114
	v_and_b32_e32 v67, 0xffff0000, v114
	v_lshlrev_b32_e32 v69, 16, v115
	v_and_b32_e32 v71, 0xffff0000, v115
	v_mul_f32_e32 v65, 0xbfb8aa3b, v65
	v_mul_f32_e32 v67, 0xbfb8aa3b, v67
	v_mul_f32_e32 v69, 0xbfb8aa3b, v69
	v_mul_f32_e32 v71, 0xbfb8aa3b, v71
	v_exp_f32_e32 v65, v65
	v_exp_f32_e32 v67, v67
	v_exp_f32_e32 v69, v69
	v_exp_f32_e32 v71, v71
	v_add_f32_e32 v65, 1.0, v65
	v_add_f32_e32 v67, 1.0, v67
	v_add_f32_e32 v69, 1.0, v69
	v_add_f32_e32 v71, 1.0, v71
	v_rcp_f32_e32 v65, v65
	v_rcp_f32_e32 v67, v67
	v_rcp_f32_e32 v69, v69
	v_rcp_f32_e32 v71, v71
	v_max_f32_e32 v110, 0x358637bd, v65
	v_max_f32_e32 v111, 0x358637bd, v67
	v_max_f32_e32 v114, 0x358637bd, v69
	v_max_f32_e32 v115, 0x358637bd, v71
	v_lshlrev_b32_e32 v65, 16, v120
	v_and_b32_e32 v67, 0xffff0000, v120
	v_lshlrev_b32_e32 v69, 16, v121
	v_and_b32_e32 v71, 0xffff0000, v121
	v_mul_f32_e32 v65, 0xbfb8aa3b, v65
	v_mul_f32_e32 v67, 0xbfb8aa3b, v67
	v_mul_f32_e32 v69, 0xbfb8aa3b, v69
	v_mul_f32_e32 v71, 0xbfb8aa3b, v71
	v_exp_f32_e32 v65, v65
	v_exp_f32_e32 v67, v67
	v_exp_f32_e32 v69, v69
	v_exp_f32_e32 v71, v71
	v_add_f32_e32 v65, 1.0, v65
	v_add_f32_e32 v67, 1.0, v67
	v_add_f32_e32 v69, 1.0, v69
	v_add_f32_e32 v71, 1.0, v71
	v_min_f32_e32 v65, 0x49742400, v65
	v_min_f32_e32 v67, 0x49742400, v67
	v_min_f32_e32 v69, 0x49742400, v69
	v_min_f32_e32 v71, 0x49742400, v71
	v_mul_f32_e32 v110, v110, v65
	v_mul_f32_e32 v111, v111, v67
	v_mul_f32_e32 v114, v114, v69
	v_mul_f32_e32 v115, v115, v71
	v_lshlrev_b32_e32 v65, 16, v122
	v_and_b32_e32 v67, 0xffff0000, v122
	v_lshlrev_b32_e32 v69, 16, v123
	v_and_b32_e32 v71, 0xffff0000, v123
	v_mul_f32_e32 v65, 0xbfb8aa3b, v65
	v_mul_f32_e32 v67, 0xbfb8aa3b, v67
	v_mul_f32_e32 v69, 0xbfb8aa3b, v69
	v_mul_f32_e32 v71, 0xbfb8aa3b, v71
	v_exp_f32_e32 v65, v65
	v_exp_f32_e32 v67, v67
	v_exp_f32_e32 v69, v69
	v_exp_f32_e32 v71, v71
	v_add_f32_e32 v65, 1.0, v65
	v_add_f32_e32 v67, 1.0, v67
	v_add_f32_e32 v69, 1.0, v69
	v_add_f32_e32 v71, 1.0, v71
	v_rcp_f32_e32 v65, v65
	v_rcp_f32_e32 v67, v67
	v_rcp_f32_e32 v69, v69
	v_rcp_f32_e32 v71, v71
	v_max_f32_e32 v120, 0x358637bd, v65
	v_max_f32_e32 v121, 0x358637bd, v67
	v_max_f32_e32 v122, 0x358637bd, v69
	v_max_f32_e32 v123, 0x358637bd, v71
	v_lshlrev_b32_e32 v65, 16, v128
	v_and_b32_e32 v67, 0xffff0000, v128
	v_lshlrev_b32_e32 v69, 16, v129
	v_and_b32_e32 v71, 0xffff0000, v129
	v_mul_f32_e32 v65, 0xbfb8aa3b, v65
	v_mul_f32_e32 v67, 0xbfb8aa3b, v67
	v_mul_f32_e32 v69, 0xbfb8aa3b, v69
	v_mul_f32_e32 v71, 0xbfb8aa3b, v71
	v_exp_f32_e32 v65, v65
	v_exp_f32_e32 v67, v67
	v_exp_f32_e32 v69, v69
	v_exp_f32_e32 v71, v71
	v_add_f32_e32 v65, 1.0, v65
	v_add_f32_e32 v67, 1.0, v67
	v_add_f32_e32 v69, 1.0, v69
	v_add_f32_e32 v71, 1.0, v71
	v_min_f32_e32 v65, 0x49742400, v65
	v_min_f32_e32 v67, 0x49742400, v67
	v_min_f32_e32 v69, 0x49742400, v69
	v_min_f32_e32 v71, 0x49742400, v71
	v_mul_f32_e32 v120, v120, v65
	v_mul_f32_e32 v121, v121, v67
	v_mul_f32_e32 v122, v122, v69
	v_mul_f32_e32 v123, v123, v71
	v_lshlrev_b32_e32 v65, 16, v130
	v_and_b32_e32 v67, 0xffff0000, v130
	v_lshlrev_b32_e32 v69, 16, v131
	v_and_b32_e32 v71, 0xffff0000, v131
	v_mul_f32_e32 v65, 0xbfb8aa3b, v65
	v_mul_f32_e32 v67, 0xbfb8aa3b, v67
	v_mul_f32_e32 v69, 0xbfb8aa3b, v69
	v_mul_f32_e32 v71, 0xbfb8aa3b, v71
	v_exp_f32_e32 v65, v65
	v_exp_f32_e32 v67, v67
	v_exp_f32_e32 v69, v69
	v_exp_f32_e32 v71, v71
	v_add_f32_e32 v65, 1.0, v65
	v_add_f32_e32 v67, 1.0, v67
	v_add_f32_e32 v69, 1.0, v69
	v_add_f32_e32 v71, 1.0, v71
	v_rcp_f32_e32 v65, v65
	v_rcp_f32_e32 v67, v67
	v_rcp_f32_e32 v69, v69
	v_rcp_f32_e32 v71, v71
	v_max_f32_e32 v128, 0x358637bd, v65
	v_max_f32_e32 v129, 0x358637bd, v67
	v_max_f32_e32 v130, 0x358637bd, v69
	v_max_f32_e32 v131, 0x358637bd, v71
	v_lshlrev_b32_e32 v65, 16, v136
	v_and_b32_e32 v67, 0xffff0000, v136
	v_lshlrev_b32_e32 v69, 16, v137
	v_and_b32_e32 v71, 0xffff0000, v137
	v_mul_f32_e32 v65, 0xbfb8aa3b, v65
	v_mul_f32_e32 v67, 0xbfb8aa3b, v67
	v_mul_f32_e32 v69, 0xbfb8aa3b, v69
	v_mul_f32_e32 v71, 0xbfb8aa3b, v71
	v_exp_f32_e32 v65, v65
	v_exp_f32_e32 v67, v67
	v_exp_f32_e32 v69, v69
	v_exp_f32_e32 v71, v71
	v_add_f32_e32 v65, 1.0, v65
	v_add_f32_e32 v67, 1.0, v67
	v_add_f32_e32 v69, 1.0, v69
	v_add_f32_e32 v71, 1.0, v71
	v_min_f32_e32 v65, 0x49742400, v65
	v_min_f32_e32 v67, 0x49742400, v67
	v_min_f32_e32 v69, 0x49742400, v69
	v_min_f32_e32 v71, 0x49742400, v71
	v_mul_f32_e32 v128, v128, v65
	v_mul_f32_e32 v129, v129, v67
	v_mul_f32_e32 v130, v130, v69
	v_mul_f32_e32 v131, v131, v71
	v_lshlrev_b32_e32 v65, 16, v138
	v_and_b32_e32 v67, 0xffff0000, v138
	v_lshlrev_b32_e32 v69, 16, v139
	v_and_b32_e32 v71, 0xffff0000, v139
	v_mul_f32_e32 v65, 0xbfb8aa3b, v65
	v_mul_f32_e32 v67, 0xbfb8aa3b, v67
	v_mul_f32_e32 v69, 0xbfb8aa3b, v69
	v_mul_f32_e32 v71, 0xbfb8aa3b, v71
	v_exp_f32_e32 v65, v65
	v_exp_f32_e32 v67, v67
	v_exp_f32_e32 v69, v69
	v_exp_f32_e32 v71, v71
	v_add_f32_e32 v65, 1.0, v65
	v_add_f32_e32 v67, 1.0, v67
	v_add_f32_e32 v69, 1.0, v69
	v_add_f32_e32 v71, 1.0, v71
	v_rcp_f32_e32 v65, v65
	v_rcp_f32_e32 v67, v67
	v_rcp_f32_e32 v69, v69
	v_rcp_f32_e32 v71, v71
	v_max_f32_e32 v136, 0x358637bd, v65
	v_max_f32_e32 v137, 0x358637bd, v67
	v_max_f32_e32 v138, 0x358637bd, v69
	v_max_f32_e32 v139, 0x358637bd, v71
	v_lshlrev_b32_e32 v65, 16, v134
	v_and_b32_e32 v67, 0xffff0000, v134
	v_lshlrev_b32_e32 v69, 16, v135
	v_and_b32_e32 v71, 0xffff0000, v135
	v_mul_f32_e32 v65, 0xbfb8aa3b, v65
	v_mul_f32_e32 v67, 0xbfb8aa3b, v67
	v_mul_f32_e32 v69, 0xbfb8aa3b, v69
	v_mul_f32_e32 v71, 0xbfb8aa3b, v71
	v_exp_f32_e32 v65, v65
	v_exp_f32_e32 v67, v67
	v_exp_f32_e32 v69, v69
	v_exp_f32_e32 v71, v71
	v_add_f32_e32 v65, 1.0, v65
	v_add_f32_e32 v67, 1.0, v67
	v_add_f32_e32 v69, 1.0, v69
	v_add_f32_e32 v71, 1.0, v71
	v_min_f32_e32 v65, 0x49742400, v65
	v_min_f32_e32 v67, 0x49742400, v67
	v_min_f32_e32 v69, 0x49742400, v69
	v_min_f32_e32 v71, 0x49742400, v71
	v_mul_f32_e32 v136, v136, v65
	v_mul_f32_e32 v137, v137, v67
	v_mul_f32_e32 v138, v138, v69
	v_mul_f32_e32 v139, v139, v71
	v_lshlrev_b32_e32 v65, 16, v132
	v_and_b32_e32 v67, 0xffff0000, v132
	v_lshlrev_b32_e32 v69, 16, v133
	v_and_b32_e32 v71, 0xffff0000, v133
	v_mul_f32_e32 v65, 0xbfb8aa3b, v65
	v_mul_f32_e32 v67, 0xbfb8aa3b, v67
	v_mul_f32_e32 v69, 0xbfb8aa3b, v69
	v_mul_f32_e32 v71, 0xbfb8aa3b, v71
	v_exp_f32_e32 v65, v65
	v_exp_f32_e32 v67, v67
	v_exp_f32_e32 v69, v69
	v_exp_f32_e32 v71, v71
	v_add_f32_e32 v65, 1.0, v65
	v_add_f32_e32 v67, 1.0, v67
	v_add_f32_e32 v69, 1.0, v69
	v_add_f32_e32 v71, 1.0, v71
	v_rcp_f32_e32 v65, v65
	v_rcp_f32_e32 v67, v67
	v_rcp_f32_e32 v69, v69
	v_rcp_f32_e32 v71, v71
	v_max_f32_e32 v134, 0x358637bd, v65
	v_max_f32_e32 v135, 0x358637bd, v67
	v_max_f32_e32 v132, 0x358637bd, v69
	v_max_f32_e32 v133, 0x358637bd, v71
	v_lshlrev_b32_e32 v65, 16, v126
	v_and_b32_e32 v67, 0xffff0000, v126
	v_lshlrev_b32_e32 v69, 16, v127
	v_and_b32_e32 v71, 0xffff0000, v127
	v_mul_f32_e32 v65, 0xbfb8aa3b, v65
	v_mul_f32_e32 v67, 0xbfb8aa3b, v67
	v_mul_f32_e32 v69, 0xbfb8aa3b, v69
	v_mul_f32_e32 v71, 0xbfb8aa3b, v71
	v_exp_f32_e32 v65, v65
	v_exp_f32_e32 v67, v67
	v_exp_f32_e32 v69, v69
	v_exp_f32_e32 v71, v71
	v_add_f32_e32 v65, 1.0, v65
	v_add_f32_e32 v67, 1.0, v67
	v_add_f32_e32 v69, 1.0, v69
	v_add_f32_e32 v71, 1.0, v71
	v_min_f32_e32 v65, 0x49742400, v65
	v_min_f32_e32 v67, 0x49742400, v67
	v_min_f32_e32 v69, 0x49742400, v69
	v_min_f32_e32 v71, 0x49742400, v71
	v_mul_f32_e32 v134, v134, v65
	v_mul_f32_e32 v135, v135, v67
	v_mul_f32_e32 v132, v132, v69
	v_mul_f32_e32 v133, v133, v71
	v_lshlrev_b32_e32 v65, 16, v124
	v_and_b32_e32 v67, 0xffff0000, v124
	v_lshlrev_b32_e32 v69, 16, v125
	v_and_b32_e32 v71, 0xffff0000, v125
	v_mul_f32_e32 v65, 0xbfb8aa3b, v65
	v_mul_f32_e32 v67, 0xbfb8aa3b, v67
	v_mul_f32_e32 v69, 0xbfb8aa3b, v69
	v_mul_f32_e32 v71, 0xbfb8aa3b, v71
	v_exp_f32_e32 v65, v65
	v_exp_f32_e32 v67, v67
	v_exp_f32_e32 v69, v69
	v_exp_f32_e32 v71, v71
	v_add_f32_e32 v65, 1.0, v65
	v_add_f32_e32 v67, 1.0, v67
	v_add_f32_e32 v69, 1.0, v69
	v_add_f32_e32 v71, 1.0, v71
	v_rcp_f32_e32 v65, v65
	v_rcp_f32_e32 v67, v67
	v_rcp_f32_e32 v69, v69
	v_rcp_f32_e32 v71, v71
	v_max_f32_e32 v126, 0x358637bd, v65
	v_max_f32_e32 v127, 0x358637bd, v67
	v_max_f32_e32 v124, 0x358637bd, v69
	v_max_f32_e32 v125, 0x358637bd, v71
	v_lshlrev_b32_e32 v65, 16, v118
	v_and_b32_e32 v67, 0xffff0000, v118
	v_lshlrev_b32_e32 v69, 16, v119
	v_and_b32_e32 v71, 0xffff0000, v119
	v_mul_f32_e32 v65, 0xbfb8aa3b, v65
	v_mul_f32_e32 v67, 0xbfb8aa3b, v67
	v_mul_f32_e32 v69, 0xbfb8aa3b, v69
	v_mul_f32_e32 v71, 0xbfb8aa3b, v71
	v_exp_f32_e32 v65, v65
	v_exp_f32_e32 v67, v67
	v_exp_f32_e32 v69, v69
	v_exp_f32_e32 v71, v71
	v_add_f32_e32 v65, 1.0, v65
	v_add_f32_e32 v67, 1.0, v67
	v_add_f32_e32 v69, 1.0, v69
	v_add_f32_e32 v71, 1.0, v71
	v_min_f32_e32 v65, 0x49742400, v65
	v_min_f32_e32 v67, 0x49742400, v67
	v_min_f32_e32 v69, 0x49742400, v69
	v_min_f32_e32 v71, 0x49742400, v71
	v_mul_f32_e32 v126, v126, v65
	v_mul_f32_e32 v127, v127, v67
	v_mul_f32_e32 v124, v124, v69
	v_mul_f32_e32 v125, v125, v71
	v_lshlrev_b32_e32 v65, 16, v116
	v_and_b32_e32 v67, 0xffff0000, v116
	v_lshlrev_b32_e32 v69, 16, v117
	v_and_b32_e32 v71, 0xffff0000, v117
	v_mul_f32_e32 v65, 0xbfb8aa3b, v65
	v_mul_f32_e32 v67, 0xbfb8aa3b, v67
	v_mul_f32_e32 v69, 0xbfb8aa3b, v69
	v_mul_f32_e32 v71, 0xbfb8aa3b, v71
	v_exp_f32_e32 v65, v65
	v_exp_f32_e32 v67, v67
	v_exp_f32_e32 v69, v69
	v_exp_f32_e32 v71, v71
	v_add_f32_e32 v65, 1.0, v65
	v_add_f32_e32 v67, 1.0, v67
	v_add_f32_e32 v69, 1.0, v69
	v_add_f32_e32 v71, 1.0, v71
	v_rcp_f32_e32 v65, v65
	v_rcp_f32_e32 v67, v67
	v_rcp_f32_e32 v69, v69
	v_rcp_f32_e32 v71, v71
	v_max_f32_e32 v118, 0x358637bd, v65
	v_max_f32_e32 v119, 0x358637bd, v67
	v_max_f32_e32 v116, 0x358637bd, v69
	v_max_f32_e32 v117, 0x358637bd, v71
	v_lshlrev_b32_e32 v65, 16, v112
	v_and_b32_e32 v67, 0xffff0000, v112
	v_lshlrev_b32_e32 v69, 16, v113
	v_and_b32_e32 v71, 0xffff0000, v113
	v_mul_f32_e32 v65, 0xbfb8aa3b, v65
	v_mul_f32_e32 v67, 0xbfb8aa3b, v67
	v_mul_f32_e32 v69, 0xbfb8aa3b, v69
	v_mul_f32_e32 v71, 0xbfb8aa3b, v71
	v_exp_f32_e32 v65, v65
	v_exp_f32_e32 v67, v67
	v_exp_f32_e32 v69, v69
	v_exp_f32_e32 v71, v71
	v_add_f32_e32 v65, 1.0, v65
	v_add_f32_e32 v67, 1.0, v67
	v_add_f32_e32 v69, 1.0, v69
	v_add_f32_e32 v71, 1.0, v71
	v_min_f32_e32 v65, 0x49742400, v65
	v_min_f32_e32 v67, 0x49742400, v67
	v_min_f32_e32 v69, 0x49742400, v69
	v_min_f32_e32 v71, 0x49742400, v71
	v_mul_f32_e32 v118, v118, v65
	v_mul_f32_e32 v119, v119, v67
	v_mul_f32_e32 v116, v116, v69
	v_mul_f32_e32 v117, v117, v71
	v_lshlrev_b32_e32 v65, 16, v108
	v_and_b32_e32 v67, 0xffff0000, v108
	v_lshlrev_b32_e32 v69, 16, v109
	v_and_b32_e32 v71, 0xffff0000, v109
	v_mul_f32_e32 v65, 0xbfb8aa3b, v65
	v_mul_f32_e32 v67, 0xbfb8aa3b, v67
	v_mul_f32_e32 v69, 0xbfb8aa3b, v69
	v_mul_f32_e32 v71, 0xbfb8aa3b, v71
	v_exp_f32_e32 v65, v65
	v_exp_f32_e32 v67, v67
	v_exp_f32_e32 v69, v69
	v_exp_f32_e32 v71, v71
	v_add_f32_e32 v65, 1.0, v65
	v_add_f32_e32 v67, 1.0, v67
	v_add_f32_e32 v69, 1.0, v69
	v_add_f32_e32 v71, 1.0, v71
	v_rcp_f32_e32 v65, v65
	v_rcp_f32_e32 v67, v67
	v_rcp_f32_e32 v69, v69
	v_rcp_f32_e32 v71, v71
	v_max_f32_e32 v112, 0x358637bd, v65
	v_max_f32_e32 v113, 0x358637bd, v67
	v_max_f32_e32 v108, 0x358637bd, v69
	v_max_f32_e32 v109, 0x358637bd, v71
	v_lshlrev_b32_e32 v65, 16, v104
	v_and_b32_e32 v67, 0xffff0000, v104
	v_lshlrev_b32_e32 v69, 16, v105
	v_and_b32_e32 v71, 0xffff0000, v105
	v_mul_f32_e32 v65, 0xbfb8aa3b, v65
	v_mul_f32_e32 v67, 0xbfb8aa3b, v67
	v_mul_f32_e32 v69, 0xbfb8aa3b, v69
	v_mul_f32_e32 v71, 0xbfb8aa3b, v71
	v_exp_f32_e32 v65, v65
	v_exp_f32_e32 v67, v67
	v_exp_f32_e32 v69, v69
	v_exp_f32_e32 v71, v71
	v_add_f32_e32 v65, 1.0, v65
	v_add_f32_e32 v67, 1.0, v67
	v_add_f32_e32 v69, 1.0, v69
	v_add_f32_e32 v71, 1.0, v71
	v_min_f32_e32 v65, 0x49742400, v65
	v_min_f32_e32 v67, 0x49742400, v67
	v_min_f32_e32 v69, 0x49742400, v69
	v_min_f32_e32 v71, 0x49742400, v71
	v_mul_f32_e32 v112, v112, v65
	v_mul_f32_e32 v113, v113, v67
	v_mul_f32_e32 v108, v108, v69
	v_mul_f32_e32 v109, v109, v71
	v_lshlrev_b32_e32 v65, 16, v100
	v_and_b32_e32 v67, 0xffff0000, v100
	v_lshlrev_b32_e32 v69, 16, v101
	v_and_b32_e32 v71, 0xffff0000, v101
	v_mul_f32_e32 v65, 0xbfb8aa3b, v65
	v_mul_f32_e32 v67, 0xbfb8aa3b, v67
	v_mul_f32_e32 v69, 0xbfb8aa3b, v69
	v_mul_f32_e32 v71, 0xbfb8aa3b, v71
	v_exp_f32_e32 v65, v65
	v_exp_f32_e32 v67, v67
	v_exp_f32_e32 v69, v69
	v_exp_f32_e32 v71, v71
	v_add_f32_e32 v65, 1.0, v65
	v_add_f32_e32 v67, 1.0, v67
	v_add_f32_e32 v69, 1.0, v69
	v_add_f32_e32 v71, 1.0, v71
	v_rcp_f32_e32 v65, v65
	v_rcp_f32_e32 v67, v67
	v_rcp_f32_e32 v69, v69
	v_rcp_f32_e32 v71, v71
	v_max_f32_e32 v104, 0x358637bd, v65
	v_max_f32_e32 v105, 0x358637bd, v67
	v_max_f32_e32 v100, 0x358637bd, v69
	v_max_f32_e32 v101, 0x358637bd, v71
	v_lshlrev_b32_e32 v65, 16, v98
	v_and_b32_e32 v67, 0xffff0000, v98
	v_lshlrev_b32_e32 v69, 16, v99
	v_and_b32_e32 v71, 0xffff0000, v99
	v_mul_f32_e32 v65, 0xbfb8aa3b, v65
	v_mul_f32_e32 v67, 0xbfb8aa3b, v67
	v_mul_f32_e32 v69, 0xbfb8aa3b, v69
	v_mul_f32_e32 v71, 0xbfb8aa3b, v71
	v_exp_f32_e32 v65, v65
	v_exp_f32_e32 v67, v67
	v_exp_f32_e32 v69, v69
	v_exp_f32_e32 v71, v71
	v_add_f32_e32 v65, 1.0, v65
	v_add_f32_e32 v67, 1.0, v67
	v_add_f32_e32 v69, 1.0, v69
	v_add_f32_e32 v71, 1.0, v71
	v_min_f32_e32 v65, 0x49742400, v65
	v_min_f32_e32 v67, 0x49742400, v67
	v_min_f32_e32 v69, 0x49742400, v69
	v_min_f32_e32 v71, 0x49742400, v71
	v_mul_f32_e32 v104, v104, v65
	v_mul_f32_e32 v105, v105, v67
	v_mul_f32_e32 v100, v100, v69
	v_mul_f32_e32 v101, v101, v71
	v_lshlrev_b32_e32 v65, 16, v96
	v_and_b32_e32 v67, 0xffff0000, v96
	v_lshlrev_b32_e32 v69, 16, v97
	v_and_b32_e32 v71, 0xffff0000, v97
	v_mul_f32_e32 v65, 0xbfb8aa3b, v65
	v_mul_f32_e32 v67, 0xbfb8aa3b, v67
	v_mul_f32_e32 v69, 0xbfb8aa3b, v69
	v_mul_f32_e32 v71, 0xbfb8aa3b, v71
	v_exp_f32_e32 v65, v65
	v_exp_f32_e32 v67, v67
	v_exp_f32_e32 v69, v69
	v_exp_f32_e32 v71, v71
	v_add_f32_e32 v65, 1.0, v65
	v_add_f32_e32 v67, 1.0, v67
	v_add_f32_e32 v69, 1.0, v69
	v_add_f32_e32 v71, 1.0, v71
	v_rcp_f32_e32 v65, v65
	v_rcp_f32_e32 v67, v67
	v_rcp_f32_e32 v69, v69
	v_rcp_f32_e32 v71, v71
	v_max_f32_e32 v98, 0x358637bd, v65
	v_max_f32_e32 v99, 0x358637bd, v67
	v_max_f32_e32 v96, 0x358637bd, v69
	v_max_f32_e32 v97, 0x358637bd, v71
	v_lshlrev_b32_e32 v65, 16, v94
	v_and_b32_e32 v67, 0xffff0000, v94
	v_lshlrev_b32_e32 v69, 16, v95
	v_and_b32_e32 v71, 0xffff0000, v95
	v_mul_f32_e32 v65, 0xbfb8aa3b, v65
	v_mul_f32_e32 v67, 0xbfb8aa3b, v67
	v_mul_f32_e32 v69, 0xbfb8aa3b, v69
	v_mul_f32_e32 v71, 0xbfb8aa3b, v71
	v_exp_f32_e32 v65, v65
	v_exp_f32_e32 v67, v67
	v_exp_f32_e32 v69, v69
	v_exp_f32_e32 v71, v71
	v_add_f32_e32 v65, 1.0, v65
	v_add_f32_e32 v67, 1.0, v67
	v_add_f32_e32 v69, 1.0, v69
	v_add_f32_e32 v71, 1.0, v71
	v_min_f32_e32 v65, 0x49742400, v65
	v_min_f32_e32 v67, 0x49742400, v67
	v_min_f32_e32 v69, 0x49742400, v69
	v_min_f32_e32 v71, 0x49742400, v71
	v_mul_f32_e32 v98, v98, v65
	v_mul_f32_e32 v99, v99, v67
	v_mul_f32_e32 v96, v96, v69
	v_mul_f32_e32 v97, v97, v71
	s_branch .LBB0_111
